# stack6 + attention output stores widened to dwordx4 via v_permlane32_swap
# baseline (speedup 1.0000x reference)
.LBB0_250:
	v_and_b32_e32 v3, 64, v158
	v_xor_b32_e32 v2, 32, v158
	v_add_u32_e32 v3, 64, v3
	s_lshl_b64 s[98:99], s[60:61], 25
	v_cmp_lt_i32_e32 vcc, v2, v3
	s_add_u32 s67, s70, s98
	s_addc_u32 s73, s71, s99
	v_cndmask_b32_e32 v2, v158, v2, vcc
	v_lshlrev_b32_e32 v91, 2, v2
	s_add_u32 s67, s67, 0xfe000000
	ds_bpermute_b32 v2, v91, v138
	s_addc_u32 s73, s73, -1
	s_cmp_eq_u32 s60, 0
	s_cselect_b32 s67, s30, s67
	s_cselect_b32 s73, s31, s73
	s_add_u32 s64, s67, s64
	s_addc_u32 s65, s73, s65
	v_mov_b32_e32 v93, v1
	s_waitcnt lgkmcnt(0)
	v_add_f32_e32 v2, v138, v2
	v_lshl_add_u64 v[96:97], s[64:65], 0, v[92:93]
	v_div_scale_f32 v3, s[64:65], v2, v2, 1.0
	v_rcp_f32_e32 v4, v3
	s_lshl_b64 s[60:61], s[60:61], 20
	s_add_u32 s60, s96, s60
	s_addc_u32 s61, s97, s61
	v_fma_f32 v5, -v3, v4, 1.0
	v_fmac_f32_e32 v4, v5, v4
	v_div_scale_f32 v5, vcc, 1.0, v2, 1.0
	v_mul_f32_e32 v6, v5, v4
	v_fma_f32 v7, -v3, v6, v5
	v_fmac_f32_e32 v6, v7, v4
	v_fma_f32 v3, -v3, v6, v5
	v_div_fmas_f32 v3, v3, v4, v6
	v_div_fixup_f32 v3, v3, v2, 1.0
	v_lshlrev_b64 v[4:5], 11, v[94:95]
	v_lshl_add_u64 v[4:5], v[96:97], 0, v[4:5]
	s_add_u32 s0, s60, s0
	s_addc_u32 s1, s61, s1
	v_lshrrev_b32_e32 v216, 5, v158
	v_lshlrev_b32_e32 v216, 3, v216
	v_mov_b32_e32 v217, 0
	v_lshl_add_u64 v[4:5], v[4:5], 0, v[216:217]
	v_mul_f32_e32 v218, v16, v3
	v_mul_f32_e32 v219, v17, v3
	v_cvt_pk_bf16_f32 v200, v218, v219
	v_mul_f32_e32 v218, v18, v3
	v_mul_f32_e32 v219, v19, v3
	v_cvt_pk_bf16_f32 v201, v218, v219
	v_mul_f32_e32 v218, v32, v3
	v_mul_f32_e32 v219, v33, v3
	v_cvt_pk_bf16_f32 v208, v218, v219
	v_mul_f32_e32 v218, v34, v3
	v_mul_f32_e32 v219, v35, v3
	v_cvt_pk_bf16_f32 v209, v218, v219
	v_mul_f32_e32 v218, v20, v3
	v_mul_f32_e32 v219, v21, v3
	v_cvt_pk_bf16_f32 v202, v218, v219
	v_mul_f32_e32 v218, v22, v3
	v_mul_f32_e32 v219, v23, v3
	v_cvt_pk_bf16_f32 v203, v218, v219
	v_mul_f32_e32 v218, v36, v3
	v_mul_f32_e32 v219, v37, v3
	v_cvt_pk_bf16_f32 v210, v218, v219
	v_mul_f32_e32 v218, v38, v3
	v_mul_f32_e32 v219, v39, v3
	v_cvt_pk_bf16_f32 v211, v218, v219
	v_mul_f32_e32 v218, v24, v3
	v_mul_f32_e32 v219, v25, v3
	v_cvt_pk_bf16_f32 v204, v218, v219
	v_mul_f32_e32 v218, v26, v3
	v_mul_f32_e32 v219, v27, v3
	v_cvt_pk_bf16_f32 v205, v218, v219
	v_mul_f32_e32 v218, v40, v3
	v_mul_f32_e32 v219, v41, v3
	v_cvt_pk_bf16_f32 v212, v218, v219
	v_mul_f32_e32 v218, v42, v3
	v_mul_f32_e32 v219, v43, v3
	v_cvt_pk_bf16_f32 v213, v218, v219
	v_mul_f32_e32 v218, v28, v3
	v_mul_f32_e32 v219, v29, v3
	v_cvt_pk_bf16_f32 v206, v218, v219
	v_mul_f32_e32 v218, v30, v3
	v_mul_f32_e32 v219, v31, v3
	v_cvt_pk_bf16_f32 v207, v218, v219
	v_mul_f32_e32 v218, v44, v3
	v_mul_f32_e32 v219, v45, v3
	v_cvt_pk_bf16_f32 v214, v218, v219
	v_mul_f32_e32 v218, v46, v3
	v_mul_f32_e32 v219, v47, v3
	v_cvt_pk_bf16_f32 v215, v218, v219
	s_nop 1
	v_permlane32_swap_b32_e32 v200, v202
	v_permlane32_swap_b32_e32 v201, v203
	v_permlane32_swap_b32_e32 v204, v206
	v_permlane32_swap_b32_e32 v205, v207
	v_permlane32_swap_b32_e32 v208, v210
	v_permlane32_swap_b32_e32 v209, v211
	v_permlane32_swap_b32_e32 v212, v214
	v_permlane32_swap_b32_e32 v213, v215
	global_store_dwordx4 v[4:5], v[200:203], off
	global_store_dwordx4 v[4:5], v[204:207], off offset:32
	global_store_dwordx4 v[4:5], v[208:211], off offset:64
	global_store_dwordx4 v[4:5], v[212:215], off offset:96
	s_and_saveexec_b64 s[60:61], s[54:55]
	s_cbranch_execz .LBB0_252
	v_log_f32_e32 v4, v2
	v_lshlrev_b64 v[2:3], 6, v[94:95]
	v_lshl_add_u64 v[2:3], s[0:1], 0, v[2:3]
	v_add_f32_e32 v0, v0, v4
	v_mul_f32_e32 v0, 0x3f317218, v0
	global_store_dword v[2:3], v0, off

.LBB0_263:
	ds_bpermute_b32 v2, v91, v93
	s_waitcnt lgkmcnt(0)
	v_add_f32_e32 v2, v93, v2
	v_div_scale_f32 v3, s[16:17], v2, v2, 1.0
	v_rcp_f32_e32 v4, v3
	s_nop 0
	v_fma_f32 v5, -v3, v4, 1.0
	v_fmac_f32_e32 v4, v5, v4
	v_div_scale_f32 v5, vcc, 1.0, v2, 1.0
	v_mul_f32_e32 v6, v5, v4
	v_fma_f32 v7, -v3, v6, v5
	v_fmac_f32_e32 v6, v7, v4
	v_fma_f32 v3, -v3, v6, v5
	v_div_fmas_f32 v3, v3, v4, v6
	v_div_fixup_f32 v3, v3, v2, 1.0
	v_lshlrev_b64 v[4:5], 11, v[94:95]
	v_lshl_add_u64 v[4:5], v[96:97], 0, v[4:5]
	v_lshrrev_b32_e32 v216, 5, v158
	v_lshlrev_b32_e32 v216, 3, v216
	v_mov_b32_e32 v217, 0
	v_lshl_add_u64 v[4:5], v[4:5], 0, v[216:217]
	v_mul_f32_e32 v218, v16, v3
	v_mul_f32_e32 v219, v17, v3
	v_cvt_pk_bf16_f32 v200, v218, v219
	v_mul_f32_e32 v218, v18, v3
	v_mul_f32_e32 v219, v19, v3
	v_cvt_pk_bf16_f32 v201, v218, v219
	v_mul_f32_e32 v218, v32, v3
	v_mul_f32_e32 v219, v33, v3
	v_cvt_pk_bf16_f32 v208, v218, v219
	v_mul_f32_e32 v218, v34, v3
	v_mul_f32_e32 v219, v35, v3
	v_cvt_pk_bf16_f32 v209, v218, v219
	v_mul_f32_e32 v218, v20, v3
	v_mul_f32_e32 v219, v21, v3
	v_cvt_pk_bf16_f32 v202, v218, v219
	v_mul_f32_e32 v218, v22, v3
	v_mul_f32_e32 v219, v23, v3
	v_cvt_pk_bf16_f32 v203, v218, v219
	v_mul_f32_e32 v218, v36, v3
	v_mul_f32_e32 v219, v37, v3
	v_cvt_pk_bf16_f32 v210, v218, v219
	v_mul_f32_e32 v218, v38, v3
	v_mul_f32_e32 v219, v39, v3
	v_cvt_pk_bf16_f32 v211, v218, v219
	v_mul_f32_e32 v218, v24, v3
	v_mul_f32_e32 v219, v25, v3
	v_cvt_pk_bf16_f32 v204, v218, v219
	v_mul_f32_e32 v218, v26, v3
	v_mul_f32_e32 v219, v27, v3
	v_cvt_pk_bf16_f32 v205, v218, v219
	v_mul_f32_e32 v218, v40, v3
	v_mul_f32_e32 v219, v41, v3
	v_cvt_pk_bf16_f32 v212, v218, v219
	v_mul_f32_e32 v218, v42, v3
	v_mul_f32_e32 v219, v43, v3
	v_cvt_pk_bf16_f32 v213, v218, v219
	v_mul_f32_e32 v218, v28, v3
	v_mul_f32_e32 v219, v29, v3
	v_cvt_pk_bf16_f32 v206, v218, v219
	v_mul_f32_e32 v218, v30, v3
	v_mul_f32_e32 v219, v31, v3
	v_cvt_pk_bf16_f32 v207, v218, v219
	v_mul_f32_e32 v218, v44, v3
	v_mul_f32_e32 v219, v45, v3
	v_cvt_pk_bf16_f32 v214, v218, v219
	v_mul_f32_e32 v218, v46, v3
	v_mul_f32_e32 v219, v47, v3
	v_cvt_pk_bf16_f32 v215, v218, v219
	s_nop 1
	v_permlane32_swap_b32_e32 v200, v202
	v_permlane32_swap_b32_e32 v201, v203
	v_permlane32_swap_b32_e32 v204, v206
	v_permlane32_swap_b32_e32 v205, v207
	v_permlane32_swap_b32_e32 v208, v210
	v_permlane32_swap_b32_e32 v209, v211
	v_permlane32_swap_b32_e32 v212, v214
	v_permlane32_swap_b32_e32 v213, v215
	global_store_dwordx4 v[4:5], v[200:203], off
	global_store_dwordx4 v[4:5], v[204:207], off offset:32
	global_store_dwordx4 v[4:5], v[208:211], off offset:64
	global_store_dwordx4 v[4:5], v[212:215], off offset:96
	s_and_saveexec_b64 s[16:17], s[54:55]
	s_cbranch_execz .LBB0_197
	v_log_f32_e32 v4, v2
	v_lshlrev_b64 v[2:3], 6, v[94:95]
	v_lshl_add_u64 v[2:3], s[0:1], 0, v[2:3]
	v_add_f32_e32 v0, v0, v4
	v_mul_f32_e32 v0, 0x3f317218, v0
	global_store_dword v[2:3], v0, off
	s_branch .LBB0_197
